# FF2 full-K epilogue: accumulators and lane address terms exchanged across lanes (ds_bpermute) so residual loads and R stores are 64-byte coalesced per lane quad
# speedup vs baseline: 1.0163x; 1.0106x over previous
; __device__ __forceinline__ float bflo(unsigned w) { return __uint_as_float(w << 16); }
; __device__ __forceinline__ float bfhi(unsigned w) { return __uint_as_float(w & 0xffff0000u); }
; #define PG8_STAGE(bufoff, gbase, voff) do { _Pragma("unroll") for (int _i = 0; _i < 2; ++_i) \
;     __builtin_amdgcn_global_load_lds((const unsigned*)((const char*)(gbase) + (voff)[_i]), (LAS unsigned*)(lds + (bufoff) + ldsw + _i * 8192), 16, 0, 0); } while (0)
; #define PG8_WAIT_V(n) asm volatile("s_waitcnt vmcnt(" #n ")" ::: "memory")
; template <class Epi>
; __device__ __forceinline__ void gemm_phase(LAS unsigned char* lds, const Gemm g, const StaticOrder& S, const Epi& E) {
;     ...
;   const char* cA = (const char*)(cur.which ? g.A2 : g.A) + (size_t)cur.pm * tstepA + (size_t)cur.kt0 * kstep;
;   const char* cB = (const char*)(cur.which ? g.Bt2 : g.Bt) + (size_t)cur.pn * tstepB + (size_t)cur.kt0 * kstep;
;   PG8_STAGE(PG8_SB(0, 0), cB, voffB); PG8_STAGE(PG8_SA(0, 0), cA, voffA); PG8_STAGE(PG8_SB(0, 1), cB + hstepB, voffB); PG8_STAGE(PG8_SA(0, 1), cA + hstepA, voffA);
;   if (wr == 1) PG8_BAR;
;   PG8_WAIT_V(4); PG8_BAR;
;   PG8_STAGE(PG8_SB(1, 0), cB + kstep, voffB); PG8_STAGE(PG8_SA(1, 0), cA + kstep, voffA); PG8_STAGE(PG8_SB(1, 1), cB + hstepB + kstep, voffB);
;   PG8_WAIT_V(6); PG8_BAR;
;   __device__ __forceinline__ void operator()(const f32x4 (&acc)[2][2][4][2], const Unit& u, int wr, int wc, int fr, int fq) const {
;     ...
;       for (int ai = 0; ai < 2; ++ai) {
;         u32x2 xr[4][2][2];
; #pragma unroll
;         for (int m = 0; m < 4; ++m)
; #pragma unroll
;           for (int bj = 0; bj < 2; ++bj)
; #pragma unroll
;             for (int n = 0; n < 2; ++n)
;               xr[m][bj][n] = *(const u32x2*)(xb + (size_t)(u.pm * 256 + ai * 128 + wr * 64 + m * 16 + fr) * 1024 + u.pn * 256 + bj * 128 + wc * 32 + 16 * n + 4 * fq);
; #pragma unroll
;         for (int m = 0; m < 4; ++m)
; #pragma unroll
;           for (int bj = 0; bj < 2; ++bj)
; #pragma unroll
;             for (int n = 0; n < 2; ++n) {
;               const size_t o = (size_t)(u.pm * 256 + ai * 128 + wr * 64 + m * 16 + fr) * 1024 + u.pn * 256 + bj * 128 + wc * 32 + 16 * n + 4 * fq;
;               const u32x2 xw = xr[m][bj][n];
;               const f32x4 x = (f32x4){bflo(xw[0]), bfhi(xw[0]), bflo(xw[1]), bfhi(xw[1])};
;               *(f32x4*)(R + o) = x * ALPHA + acc[ai][bj][m][n];
;             }
.LBB0_3867:
	s_lshl_b32 s2, s0, 6
	s_lshl_b32 s3, s0, 13
	s_lshl_b32 s0, s1, 5
	s_and_b32 s10, s0, 0x60
	s_add_i32 m0, s30, 0x18000
	v_lshl_add_u64 v[6:7], v[6:7], 0, s[16:17]
	s_lshl_b32 s11, s10, 7
	s_waitcnt vmcnt(4)
	s_barrier
	global_load_lds_dwordx4 v[6:7], off
	v_lshl_add_u64 v[4:5], v[4:5], 0, s[16:17]
	s_add_i32 m0, s30, 0x1a000
	s_add_i32 s36, s30, 0x8000
	s_add_i32 s37, s30, 0xa000
	global_load_lds_dwordx4 v[4:5], off
	v_lshl_add_u64 v[2:3], v[2:3], 0, s[16:17]
	s_mov_b32 m0, s36
	s_add_u32 s0, s14, 0x104080
	global_load_lds_dwordx4 v[2:3], off
	v_lshl_add_u64 v[0:1], v[0:1], 0, s[16:17]
	s_mov_b32 m0, s37
	s_addc_u32 s1, s15, 0
	global_load_lds_dwordx4 v[0:1], off
	s_add_i32 m0, s30, 0x1c000
	v_lshl_add_u64 v[0:1], s[0:1], 0, v[130:131]
	global_load_lds_dwordx4 v[0:1], off
	v_lshl_add_u64 v[0:1], s[0:1], 0, v[132:133]
	s_add_i32 m0, s30, 0x1e000
	s_lshl_b32 s0, s10, 2
	global_load_lds_dwordx4 v[0:1], off
	v_and_b32_e32 v0, 15, v8
	v_or_b32_e32 v135, s2, v0
	s_addk_i32 s2, 0x8000
	s_add_u32 s0, s6, s0
	s_addc_u32 s1, s7, 0
	s_add_u32 s38, s0, 0x1e482000
	s_addc_u32 s39, s1, 0
	s_lshl_b32 s0, s10, 1
	v_bfe_u32 v1, v8, 4, 2
	s_add_u32 s0, s6, s0
	v_lshlrev_b32_e32 v2, 4, v1
	v_lshlrev_b32_e32 v3, 2, v8
	s_addc_u32 s1, s7, 0
	v_lshlrev_b32_e32 v16, 3, v1
	v_lshl_or_b32 v2, v0, 6, v2
	v_and_b32_e32 v3, 32, v3
	v_or_b32_e32 v171, s2, v0
	v_lshlrev_b32_e32 v134, 2, v1
	v_lshl_add_u64 v[0:1], s[0:1], 0, v[16:17]
	s_mov_b64 s[0:1], 0x39c0000
	s_movk_i32 s2, 0x1040
	v_bitop3_b32 v4, v2, s3, v3 bitop3:0xde
	v_lshl_add_u64 v[136:137], v[0:1], 0, s[0:1]
	v_lshrrev_b32_e32 v1, 1, v9
	v_mul_lo_u32 v0, v11, s2
	s_mov_b32 s3, 0x10400
	v_mad_u64_u32 v[0:1], s[0:1], v1, s3, v[0:1]
	v_or_b32_e32 v0, v0, v10
	v_add_lshl_u32 v16, v0, v12, 1
	v_lshrrev_b32_e32 v1, 1, v13
	v_mul_lo_u32 v0, v15, s2
	v_mad_u64_u32 v[0:1], s[0:1], v1, s3, v[0:1]
	v_readlane_b32 s0, v255, 20
	s_waitcnt vmcnt(6)
	s_mov_b64 s[6:7], 0x104080
	v_or_b32_e32 v0, v0, v14
	v_readlane_b32 s1, v255, 21
	s_lshl_b32 s0, s10, 2
	v_lshl_add_u64 v[138:139], v[16:17], 0, s[6:7]
	v_add_lshl_u32 v16, v0, v18, 1
	v_writelane_b32 v255, s0, 20
	v_bitop3_b32 v170, v2, s11, v3 bitop3:0xde
	v_or_b32_e32 v172, 16, v171
	v_or_b32_e32 v173, 32, v171
	v_or_b32_e32 v174, 48, v171
	v_or_b32_e32 v175, 16, v135
	v_or_b32_e32 v176, 32, v135
	v_or_b32_e32 v177, 48, v135
	v_and_b32_e32 v200, 3, v252
	v_lshlrev_b32_e32 v200, 4, v200
	v_and_b32_e32 v201, 12, v252
	v_bfe_u32 v202, v252, 4, 2
	v_or3_b32 v200, v200, v201, v202
	v_lshlrev_b32_e32 v200, 2, v200
	ds_bpermute_b32 v135, v200, v135
	ds_bpermute_b32 v175, v200, v175
	ds_bpermute_b32 v176, v200, v176
	ds_bpermute_b32 v177, v200, v177
	ds_bpermute_b32 v136, v200, v136
	ds_bpermute_b32 v137, v200, v137
	s_waitcnt lgkmcnt(0)
	v_lshl_add_u64 v[140:141], v[16:17], 0, s[6:7]
	s_mov_b32 s40, 0
	v_add_u32_e32 v178, 0, v4
	v_writelane_b32 v255, s1, 21
	s_barrier
	s_branch .LBB0_3870

; __device__ __forceinline__ float bflo(unsigned w) { return __uint_as_float(w << 16); }
; __device__ __forceinline__ float bfhi(unsigned w) { return __uint_as_float(w & 0xffff0000u); }
;   __device__ __forceinline__ void operator()(const f32x4 (&acc)[2][2][4][2], const Unit& u, int wr, int wc, int fr, int fq) const {
;     ...
;       for (int ai = 0; ai < 2; ++ai) {
;         u32x2 xr[4][2][2];
; #pragma unroll
;         for (int m = 0; m < 4; ++m)
; #pragma unroll
;           for (int bj = 0; bj < 2; ++bj)
; #pragma unroll
;             for (int n = 0; n < 2; ++n)
;               xr[m][bj][n] = *(const u32x2*)(xb + (size_t)(u.pm * 256 + ai * 128 + wr * 64 + m * 16 + fr) * 1024 + u.pn * 256 + bj * 128 + wc * 32 + 16 * n + 4 * fq);
; #pragma unroll
;         for (int m = 0; m < 4; ++m)
; #pragma unroll
;           for (int bj = 0; bj < 2; ++bj)
; #pragma unroll
;             for (int n = 0; n < 2; ++n) {
;               const size_t o = (size_t)(u.pm * 256 + ai * 128 + wr * 64 + m * 16 + fr) * 1024 + u.pn * 256 + bj * 128 + wc * 32 + 16 * n + 4 * fq;
;               const u32x2 xw = xr[m][bj][n];
;               const f32x4 x = (f32x4){bflo(xw[0]), bfhi(xw[0]), bflo(xw[1]), bfhi(xw[1])};
;               *(f32x4*)(R + o) = x * ALPHA + acc[ai][bj][m][n];
;             }
.LBB0_3887:
	s_nop 7
	v_and_b32_e32 v200, 3, v252
	v_lshlrev_b32_e32 v200, 4, v200
	v_and_b32_e32 v201, 12, v252
	v_bfe_u32 v202, v252, 4, 2
	v_or3_b32 v200, v200, v201, v202
	v_lshlrev_b32_e32 v200, 2, v200
	ds_bpermute_b32 v16, v200, v16
	ds_bpermute_b32 v0, v200, v0
	ds_bpermute_b32 v1, v200, v1
	ds_bpermute_b32 v2, v200, v2
	ds_bpermute_b32 v3, v200, v3
	ds_bpermute_b32 v4, v200, v4
	ds_bpermute_b32 v5, v200, v5
	ds_bpermute_b32 v6, v200, v6
	ds_bpermute_b32 v7, v200, v7
	ds_bpermute_b32 v8, v200, v8
	ds_bpermute_b32 v9, v200, v9
	ds_bpermute_b32 v10, v200, v10
	s_waitcnt lgkmcnt(0)
	ds_bpermute_b32 v11, v200, v11
	ds_bpermute_b32 v12, v200, v12
	ds_bpermute_b32 v13, v200, v13
	ds_bpermute_b32 v14, v200, v14
	ds_bpermute_b32 v15, v200, v15
	ds_bpermute_b32 v18, v200, v18
	ds_bpermute_b32 v19, v200, v19
	ds_bpermute_b32 v20, v200, v20
	ds_bpermute_b32 v21, v200, v21
	ds_bpermute_b32 v22, v200, v22
	ds_bpermute_b32 v23, v200, v23
	ds_bpermute_b32 v24, v200, v24
	s_waitcnt lgkmcnt(0)
	ds_bpermute_b32 v25, v200, v25
	ds_bpermute_b32 v26, v200, v26
	ds_bpermute_b32 v27, v200, v27
	ds_bpermute_b32 v28, v200, v28
	ds_bpermute_b32 v29, v200, v29
	ds_bpermute_b32 v30, v200, v30
	ds_bpermute_b32 v31, v200, v31
	ds_bpermute_b32 v32, v200, v32
	ds_bpermute_b32 v33, v200, v33
	ds_bpermute_b32 v34, v200, v34
	ds_bpermute_b32 v35, v200, v35
	ds_bpermute_b32 v36, v200, v36
	s_waitcnt lgkmcnt(0)
	ds_bpermute_b32 v37, v200, v37
	ds_bpermute_b32 v38, v200, v38
	ds_bpermute_b32 v39, v200, v39
	ds_bpermute_b32 v40, v200, v40
	ds_bpermute_b32 v41, v200, v41
	ds_bpermute_b32 v42, v200, v42
	ds_bpermute_b32 v43, v200, v43
	ds_bpermute_b32 v44, v200, v44
	ds_bpermute_b32 v45, v200, v45
	ds_bpermute_b32 v46, v200, v46
	ds_bpermute_b32 v47, v200, v47
	ds_bpermute_b32 v48, v200, v48
	s_waitcnt lgkmcnt(0)
	ds_bpermute_b32 v49, v200, v49
	ds_bpermute_b32 v50, v200, v50
	ds_bpermute_b32 v51, v200, v51
	ds_bpermute_b32 v52, v200, v52
	ds_bpermute_b32 v53, v200, v53
	ds_bpermute_b32 v54, v200, v54
	ds_bpermute_b32 v55, v200, v55
	ds_bpermute_b32 v56, v200, v56
	ds_bpermute_b32 v57, v200, v57
	ds_bpermute_b32 v58, v200, v58
	ds_bpermute_b32 v59, v200, v59
	ds_bpermute_b32 v60, v200, v60
	s_waitcnt lgkmcnt(0)
	ds_bpermute_b32 v61, v200, v61
	ds_bpermute_b32 v62, v200, v62
	ds_bpermute_b32 v63, v200, v63
	ds_bpermute_b32 v64, v200, v64
	ds_bpermute_b32 v65, v200, v65
	ds_bpermute_b32 v66, v200, v66
	ds_bpermute_b32 v67, v200, v67
	ds_bpermute_b32 v68, v200, v68
	ds_bpermute_b32 v69, v200, v69
	ds_bpermute_b32 v70, v200, v70
	ds_bpermute_b32 v71, v200, v71
	ds_bpermute_b32 v72, v200, v72
	s_waitcnt lgkmcnt(0)
	ds_bpermute_b32 v73, v200, v73
	ds_bpermute_b32 v74, v200, v74
	ds_bpermute_b32 v75, v200, v75
	ds_bpermute_b32 v76, v200, v76
	ds_bpermute_b32 v77, v200, v77
	ds_bpermute_b32 v78, v200, v78
	ds_bpermute_b32 v79, v200, v79
	ds_bpermute_b32 v80, v200, v80
	ds_bpermute_b32 v81, v200, v81
	ds_bpermute_b32 v82, v200, v82
	ds_bpermute_b32 v83, v200, v83
	ds_bpermute_b32 v84, v200, v84
	s_waitcnt lgkmcnt(0)
	ds_bpermute_b32 v85, v200, v85
	ds_bpermute_b32 v86, v200, v86
	ds_bpermute_b32 v87, v200, v87
	ds_bpermute_b32 v88, v200, v88
	ds_bpermute_b32 v89, v200, v89
	ds_bpermute_b32 v90, v200, v90
	ds_bpermute_b32 v91, v200, v91
	ds_bpermute_b32 v92, v200, v92
	ds_bpermute_b32 v93, v200, v93
	ds_bpermute_b32 v94, v200, v94
	ds_bpermute_b32 v95, v200, v95
	ds_bpermute_b32 v96, v200, v96
	s_waitcnt lgkmcnt(0)
	ds_bpermute_b32 v97, v200, v97
	ds_bpermute_b32 v98, v200, v98
	ds_bpermute_b32 v99, v200, v99
	ds_bpermute_b32 v100, v200, v100
	ds_bpermute_b32 v101, v200, v101
	ds_bpermute_b32 v102, v200, v102
	ds_bpermute_b32 v103, v200, v103
	ds_bpermute_b32 v104, v200, v104
	ds_bpermute_b32 v105, v200, v105
	ds_bpermute_b32 v106, v200, v106
	ds_bpermute_b32 v107, v200, v107
	ds_bpermute_b32 v108, v200, v108
	s_waitcnt lgkmcnt(0)
	ds_bpermute_b32 v109, v200, v109
	ds_bpermute_b32 v110, v200, v110
	ds_bpermute_b32 v111, v200, v111
	ds_bpermute_b32 v112, v200, v112
	ds_bpermute_b32 v113, v200, v113
	ds_bpermute_b32 v114, v200, v114
	ds_bpermute_b32 v115, v200, v115
	ds_bpermute_b32 v116, v200, v116
	ds_bpermute_b32 v117, v200, v117
	ds_bpermute_b32 v118, v200, v118
	ds_bpermute_b32 v119, v200, v119
	ds_bpermute_b32 v120, v200, v120
	s_waitcnt lgkmcnt(0)
	ds_bpermute_b32 v121, v200, v121
	ds_bpermute_b32 v122, v200, v122
	ds_bpermute_b32 v123, v200, v123
	ds_bpermute_b32 v124, v200, v124
	ds_bpermute_b32 v125, v200, v125
	ds_bpermute_b32 v126, v200, v126
	ds_bpermute_b32 v127, v200, v127
	ds_bpermute_b32 v128, v200, v128
	ds_bpermute_b32 v129, v200, v129
	s_waitcnt lgkmcnt(0)
	s_branch .LBB0_3868
